# fgate: 64-row chunks remapped so each XCD scans the row panels it owns in the GEMM phases (L2-resident xb)
# baseline (speedup 1.0000x reference)
; #define LAS __attribute__((address_space(3)))
; __device__ __forceinline__ void fgate_phase(const bfr* x, const float* wf, const float* bfg, float* cl, float* ctot, LAS float* scr, int bx, int G, int tid, int lane, int wave) {
;     for (int chunk = bx; chunk < M / 64; chunk += G) {
; #pragma unroll 1
;         for (int j = 0; j < 8; j += 2) { const int row = chunk * 64 + wave * 8 + j; typedef unsigned u32x2 __attribute__((ext_vector_type(2))); const u32x2* xa = (const u32x2*)(x + (size_t)row * D) + lane; const u32x2* xb2 = xa + D / 4; f32x4 va[4], vb[4]; float r[18]; int zo = 0; asm volatile("" : "+v"(zo));
; #pragma unroll
;             for (int jj = 0; jj < 4; ++jj) { const u32x2 wa = xa[64 * jj], wb = xb2[64 * jj]; va[jj] = (f32x4){bf_lo(wa.x), bf_hi(wa.x), bf_lo(wa.y), bf_hi(wa.y)}; vb[jj] = (f32x4){bf_lo(wb.x), bf_hi(wb.x), bf_lo(wb.y), bf_hi(wb.y)}; }
;             r[16] = 0.f; r[17] = 0.f;
; #pragma unroll
;             for (int jj = 0; jj < 4; ++jj) { r[16] += (va[jj].x * va[jj].x + va[jj].y * va[jj].y) + (va[jj].z * va[jj].z + va[jj].w * va[jj].w); r[17] += (vb[jj].x * vb[jj].x + vb[jj].y * vb[jj].y) + (vb[jj].z * vb[jj].z + vb[jj].w * vb[jj].w); }
; #pragma unroll
;             for (int h = 0; h < NH; ++h) { const f32x4* wr = (const f32x4*)(wf + h * D) + lane + zo; float da = 0.f, db = 0.f;
.LBB0_421:
	s_cmpk_gt_i32 s48, 0xff
	s_cbranch_scc1 .LBB0_430
	s_load_dwordx2 s[4:5], s[0:1], 0x40
	v_lshlrev_b32_e32 v0, 3, v158
	s_waitcnt lgkmcnt(0)
	v_mov_b32_e32 v1, 0
	v_lshl_add_u64 v[28:29], s[8:9], 0, v[0:1]
	v_lshlrev_b32_e32 v0, 4, v158
	v_lshl_add_u64 v[2:3], s[6:7], 0, v[0:1]
	s_mov_b64 s[2:3], 0x3c0000
	s_add_u32 s50, s6, 0x380000
	v_lshl_add_u64 v[30:31], v[2:3], 0, s[2:3]
	v_lshlrev_b32_e32 v2, 2, v128
	s_addc_u32 s51, s7, 0
	s_ashr_i32 s33, s39, 3
	v_and_b32_e32 v0, 28, v2
	s_and_b32 s39, s33, -8
	v_lshl_add_u64 v[32:33], s[4:5], 0, v[0:1]
	v_lshlrev_b32_e32 v1, 2, v158
	s_lshl_b32 s33, s33, 5
	v_xor_b32_e32 v89, 4, v1
	v_xor_b32_e32 v90, 8, v1
	v_xor_b32_e32 v91, 16, v1
	v_xor_b32_e32 v92, 32, v1
	v_xor_b32_e32 v93, 64, v1
	v_xor_b32_e32 v94, 0x80, v1
	s_and_b32 s33, s33, 0xffffff00
	v_and_b32_e32 v1, 0xe0, v1
	v_or3_b32 v0, s33, v1, v0
	s_lshl_b32 s33, s38, 6
	v_readlane_b32 s38, v252, 0
	v_add_u32_e32 v37, 0, v2
	v_lshlrev_b64 v[2:3], 16, v[128:129]
	s_lshl_b32 s38, s38, 6
	v_lshl_add_u64 v[2:3], s[6:7], 0, v[2:3]
	s_mov_b64 s[6:7], 0x300000
	s_add_i32 s33, s33, s38
	v_cmp_gt_u32_e32 vcc, 16, v158
	v_cmp_gt_u32_e64 s[2:3], 8, v158
	v_cmp_gt_i32_e64 s[4:5], 8, v128
	v_lshl_add_u64 v[34:35], v[2:3], 0, s[6:7]
	v_lshlrev_b32_e32 v88, 8, v128
	v_cmp_eq_u32_e64 s[6:7], 1, v158
	v_cmp_eq_u32_e64 s[8:9], 2, v158
	v_cmp_eq_u32_e64 s[10:11], 3, v158
	v_cmp_eq_u32_e64 s[12:13], 4, v158
	v_cmp_eq_u32_e64 s[14:15], 5, v158
	v_cmp_eq_u32_e64 s[16:17], 6, v158
	v_cmp_eq_u32_e64 s[18:19], 7, v158
	v_cmp_eq_u32_e64 s[20:21], 8, v158
	v_cmp_eq_u32_e64 s[22:23], 9, v158
	v_cmp_eq_u32_e64 s[24:25], 10, v158
	v_cmp_eq_u32_e64 s[26:27], 11, v158
	v_cmp_eq_u32_e64 s[28:29], 12, v158
	v_cmp_eq_u32_e64 s[30:31], 13, v158
	v_cmp_eq_u32_e64 s[34:35], 14, v158
	v_cmp_eq_u32_e64 s[36:37], 15, v158
	v_add_u32_e32 v95, 0, v0
	s_add_i32 s33, s33, s39
	s_lshl_b32 s49, s56, 6
	s_movk_i32 s57, 0x1000
	s_movk_i32 s58, 0x2000
	s_movk_i32 s59, 0x3000
	s_movk_i32 s60, 0x4000
	s_movk_i32 s61, 0x5000
	s_movk_i32 s62, 0x6000
	s_movk_i32 s63, 0x7000
	s_mov_b32 s52, 0x3a800000
	s_mov_b32 s64, 0x800000
	s_mov_b32 s65, 0xbfb8aa3b
	v_mov_b32_e32 v36, 0x358637bd
	s_and_b32 s38, s48, 7
	s_lshl_b32 s38, s38, 5
	s_lshr_b32 s39, s48, 3
	s_add_i32 s38, s38, s39
	s_sub_i32 s39, s38, s48
	s_lshl_b32 s39, s39, 6
	s_add_i32 s33, s33, s39
	s_mov_b32 s48, s38
	s_branch .LBB0_424

; #define LAS __attribute__((address_space(3)))
; __device__ __forceinline__ void fgate_phase(const bfr* x, const float* wf, const float* bfg, float* cl, float* ctot, LAS float* scr, int bx, int G, int tid, int lane, int wave) {
;     for (int chunk = bx; chunk < M / 64; chunk += G) {
; #pragma unroll 1
;         for (int j = 0; j < 8; j += 2) { const int row = chunk * 64 + wave * 8 + j; typedef unsigned u32x2 __attribute__((ext_vector_type(2))); const u32x2* xa = (const u32x2*)(x + (size_t)row * D) + lane; const u32x2* xb2 = xa + D / 4; f32x4 va[4], vb[4]; float r[18]; int zo = 0; asm volatile("" : "+v"(zo));
; #pragma unroll
;             for (int jj = 0; jj < 4; ++jj) { const u32x2 wa = xa[64 * jj], wb = xb2[64 * jj]; va[jj] = (f32x4){bf_lo(wa.x), bf_hi(wa.x), bf_lo(wa.y), bf_hi(wa.y)}; vb[jj] = (f32x4){bf_lo(wb.x), bf_hi(wb.x), bf_lo(wb.y), bf_hi(wb.y)}; }
;             r[16] = 0.f; r[17] = 0.f;
; #pragma unroll
;             for (int jj = 0; jj < 4; ++jj) { r[16] += (va[jj].x * va[jj].x + va[jj].y * va[jj].y) + (va[jj].z * va[jj].z + va[jj].w * va[jj].w); r[17] += (vb[jj].x * vb[jj].x + vb[jj].y * vb[jj].y) + (vb[jj].z * vb[jj].z + vb[jj].w * vb[jj].w); }
; #pragma unroll
;             for (int h = 0; h < NH; ++h) { const f32x4* wr = (const f32x4*)(wf + h * D) + lane + zo; float da = 0.f, db = 0.f;
.LBB0_1456:
	s_cmpk_gt_i32 s48, 0xff
	s_cbranch_scc1 .LBB0_1465
	s_load_dwordx2 s[4:5], s[0:1], 0x40
	v_lshlrev_b32_e32 v0, 3, v158
	s_waitcnt lgkmcnt(0)
	v_mov_b32_e32 v1, 0
	v_lshl_add_u64 v[28:29], s[8:9], 0, v[0:1]
	v_lshlrev_b32_e32 v0, 4, v158
	v_lshl_add_u64 v[2:3], s[6:7], 0, v[0:1]
	s_mov_b64 s[2:3], 0x3c8000
	s_add_u32 s50, s6, 0x380000
	v_lshl_add_u64 v[30:31], v[2:3], 0, s[2:3]
	v_lshlrev_b32_e32 v2, 2, v128
	s_addc_u32 s51, s7, 0
	s_ashr_i32 s33, s39, 3
	v_and_b32_e32 v0, 28, v2
	s_and_b32 s39, s33, -8
	v_lshl_add_u64 v[32:33], s[4:5], 0, v[0:1]
	v_lshlrev_b32_e32 v1, 2, v158
	s_lshl_b32 s33, s33, 5
	v_xor_b32_e32 v89, 4, v1
	v_xor_b32_e32 v90, 8, v1
	v_xor_b32_e32 v91, 16, v1
	v_xor_b32_e32 v92, 32, v1
	v_xor_b32_e32 v93, 64, v1
	v_xor_b32_e32 v94, 0x80, v1
	s_and_b32 s33, s33, 0xffffff00
	v_and_b32_e32 v1, 0xe0, v1
	v_or3_b32 v0, s33, v1, v0
	s_lshl_b32 s33, s38, 6
	v_readlane_b32 s38, v252, 0
	v_add_u32_e32 v37, 0, v2
	v_lshlrev_b64 v[2:3], 16, v[128:129]
	s_lshl_b32 s38, s38, 6
	v_lshl_add_u64 v[2:3], s[6:7], 0, v[2:3]
	s_mov_b64 s[6:7], 0x300000
	s_add_i32 s33, s33, s38
	v_cmp_gt_u32_e32 vcc, 16, v158
	v_cmp_gt_u32_e64 s[2:3], 8, v158
	v_cmp_gt_i32_e64 s[4:5], 8, v128
	v_lshl_add_u64 v[34:35], v[2:3], 0, s[6:7]
	v_lshlrev_b32_e32 v88, 8, v128
	v_cmp_eq_u32_e64 s[6:7], 1, v158
	v_cmp_eq_u32_e64 s[8:9], 2, v158
	v_cmp_eq_u32_e64 s[10:11], 3, v158
	v_cmp_eq_u32_e64 s[12:13], 4, v158
	v_cmp_eq_u32_e64 s[14:15], 5, v158
	v_cmp_eq_u32_e64 s[16:17], 6, v158
	v_cmp_eq_u32_e64 s[18:19], 7, v158
	v_cmp_eq_u32_e64 s[20:21], 8, v158
	v_cmp_eq_u32_e64 s[22:23], 9, v158
	v_cmp_eq_u32_e64 s[24:25], 10, v158
	v_cmp_eq_u32_e64 s[26:27], 11, v158
	v_cmp_eq_u32_e64 s[28:29], 12, v158
	v_cmp_eq_u32_e64 s[30:31], 13, v158
	v_cmp_eq_u32_e64 s[34:35], 14, v158
	v_cmp_eq_u32_e64 s[36:37], 15, v158
	v_add_u32_e32 v95, 0, v0
	s_add_i32 s33, s33, s39
	s_lshl_b32 s49, s56, 6
	s_movk_i32 s57, 0x1000
	s_movk_i32 s58, 0x2000
	s_movk_i32 s59, 0x3000
	s_movk_i32 s60, 0x4000
	s_movk_i32 s61, 0x5000
	s_movk_i32 s62, 0x6000
	s_movk_i32 s63, 0x7000
	s_mov_b32 s52, 0x3a800000
	s_mov_b32 s64, 0x800000
	s_mov_b32 s65, 0xbfb8aa3b
	v_mov_b32_e32 v36, 0x358637bd
	s_and_b32 s38, s48, 7
	s_lshl_b32 s38, s38, 5
	s_lshr_b32 s39, s48, 3
	s_add_i32 s38, s38, s39
	s_sub_i32 s39, s38, s48
	s_lshl_b32 s39, s39, 6
	s_add_i32 s33, s33, s39
	s_mov_b32 s48, s38
	s_branch .LBB0_1459
